# v43 + GEMM loop back edge: k-offset update and loop compare moved ahead of the last wait/barrier so only s_barrier + branch follow the final MFMA block
# speedup vs baseline: 1.0012x; 1.0012x over previous
; #define LDA(dst, b, h) _Pragma("unroll") for (int m = 0; m < 4; ++m) _Pragma("unroll") for (int k = 0; k < 2; ++k) \
;     dst[m][k] = *reinterpret_cast<const bf16x8*>((char*)SA(b, h) + lds_byte(wr * 64 + m * 16 + fr, k * 32 + fq * 8))
; #define LDB(dst, b, h) _Pragma("unroll") for (int n = 0; n < 2; ++n) _Pragma("unroll") for (int k = 0; k < 2; ++k) \
;     dst[n][k] = *reinterpret_cast<const bf16x8*>((char*)SB(b, h) + lds_byte(wc * 32 + n * 16 + fr, k * 32 + fq * 8))
; #define MMA(ai, bj, At_, Bt_) do { __builtin_amdgcn_s_setprio(1); \
;     _Pragma("unroll") for (int m = 0; m < 4; ++m) _Pragma("unroll") for (int n = 0; n < 2; ++n) _Pragma("unroll") for (int k = 0; k < 2; ++k) \
;       acc[ai][bj][m][n] = __builtin_amdgcn_mfma_f32_16x16x32_bf16(Bt_[n][k], At_[m][k], acc[ai][bj][m][n], 0, 0, 0); \
;     __builtin_amdgcn_s_setprio(0); } while (0)
; #define WAIT_V(n) asm volatile("s_waitcnt vmcnt(" #n ")" ::: "memory")
; #define WAIT_L(n) asm volatile("s_waitcnt lgkmcnt(" #n ")" ::: "memory")
; #define BAR __builtin_amdgcn_s_barrier()
; #define SCHED __builtin_amdgcn_sched_barrier(0)
; __device__ __forceinline__ void gemm_tile(const TileDesc& td, unsigned char* lds) {
;     ...
;     for (int t = 0; t < nt - 2; t += 2) {
;         LDB(B0, 0, 0); SCHED; LDA(At, 0, 0); STAGE(SA(1, 1), A, lda, brow + HALF, t + 1);
;         WAIT_L(8); BAR; WAIT_L(0); MMA(0, 0, At, B0); BAR; SCHED;
;         LDB(B1, 0, 1); STAGE(SB(0, 0), Bt, ldb, bcol, t + 2);
;         BAR; WAIT_L(0); MMA(0, 1, At, B1); BAR;
;         LDA(At, 0, 1); STAGE(SA(0, 0), A, lda, brow, t + 2);
;         BAR; WAIT_L(0); MMA(1, 0, At, B0); BAR; SCHED;
;         STAGE(SB(0, 1), Bt, ldb, bcol + HALF, t + 2);
;         WAIT_V(6); BAR; MMA(1, 1, At, B1); BAR;
.LBB0_247:
	ds_read_b128 v[190:193], v183
	ds_read_b128 v[194:197], v183 offset:1024
	ds_read_b128 v[198:201], v183 offset:2048
	ds_read_b128 v[202:205], v183 offset:3072
	s_add_u32 s7, s4, s78
	s_addc_u32 s62, s5, s79
	s_add_u32 s30, s7, 0x80
	v_add_u32_e32 v162, 0xc000, v139
	s_addc_u32 s31, s62, 0
	v_readfirstlane_b32 s63, v162
	v_add_u32_e32 v252, v182, v154
	v_lshl_add_u64 v[160:161], s[30:31], 0, v[128:129]
	s_mov_b32 m0, s63
	v_add_u32_e32 v162, 0xe000, v139
	ds_read_b128 v[206:209], v252
	ds_read_b128 v[210:213], v252 offset:1024
	ds_read_b128 v[214:217], v184
	ds_read_b128 v[218:221], v184 offset:1024
	ds_read_b128 v[222:225], v185
	ds_read_b128 v[226:229], v185 offset:1024
	ds_read_b128 v[230:233], v186
	ds_read_b128 v[234:237], v186 offset:1024
	global_load_lds_dwordx4 v[160:161], off
	v_lshl_add_u64 v[160:161], s[30:31], 0, v[130:131]
	v_readfirstlane_b32 s30, v162
	s_mov_b32 m0, s30
	s_nop 0
	global_load_lds_dwordx4 v[160:161], off
	s_waitcnt lgkmcnt(8)
	s_barrier
	s_waitcnt lgkmcnt(0)
	v_mfma_f32_16x16x32_bf16 v[100:103], v[190:193], v[206:209], v[100:103]
	v_mfma_f32_16x16x32_bf16 v[124:127], v[198:201], v[206:209], v[124:127]
	v_mfma_f32_16x16x32_bf16 v[120:123], v[190:193], v[214:217], v[120:123]
	v_mfma_f32_16x16x32_bf16 v[116:119], v[198:201], v[214:217], v[116:119]
	v_mfma_f32_16x16x32_bf16 v[112:115], v[190:193], v[222:225], v[112:115]
	v_mfma_f32_16x16x32_bf16 v[108:111], v[198:201], v[222:225], v[108:111]
	v_mfma_f32_16x16x32_bf16 v[104:107], v[190:193], v[230:233], v[104:107]
	v_mfma_f32_16x16x32_bf16 v[96:99], v[198:201], v[230:233], v[96:99]
	v_mfma_f32_16x16x32_bf16 v[100:103], v[194:197], v[210:213], v[100:103]
	v_mfma_f32_16x16x32_bf16 v[124:127], v[202:205], v[210:213], v[124:127]
	v_mfma_f32_16x16x32_bf16 v[120:123], v[194:197], v[218:221], v[120:123]
	v_mfma_f32_16x16x32_bf16 v[116:119], v[202:205], v[218:221], v[116:119]
	v_mfma_f32_16x16x32_bf16 v[112:115], v[194:197], v[226:229], v[112:115]
	v_mfma_f32_16x16x32_bf16 v[108:111], v[202:205], v[226:229], v[108:111]
	v_mfma_f32_16x16x32_bf16 v[104:107], v[194:197], v[234:237], v[104:107]
	v_mfma_f32_16x16x32_bf16 v[96:99], v[202:205], v[234:237], v[96:99]
	s_barrier
	s_add_i32 s3, s3, 2
	s_add_u32 s63, s18, s78
	s_addc_u32 s65, s19, s79
	s_add_u32 s30, s63, 0x100
	s_addc_u32 s31, s65, 0
	v_readfirstlane_b32 s66, v152
	v_lshl_add_u64 v[168:169], s[30:31], 0, v[132:133]
	s_mov_b32 m0, s66
	ds_read_b128 v[238:241], v187
	ds_read_b128 v[242:245], v187 offset:1024
	ds_read_b128 v[246:249], v187 offset:2048
	ds_read_b128 v[160:163], v187 offset:3072
	global_load_lds_dwordx4 v[168:169], off
	v_lshl_add_u64 v[168:169], s[30:31], 0, v[136:137]
	v_readfirstlane_b32 s30, v153
	s_mov_b32 m0, s30
	s_nop 0
	global_load_lds_dwordx4 v[168:169], off
	s_barrier
	s_waitcnt lgkmcnt(0)
	v_mfma_f32_16x16x32_bf16 v[92:95], v[238:241], v[206:209], v[92:95]
	v_mfma_f32_16x16x32_bf16 v[88:91], v[246:249], v[206:209], v[88:91]
	v_mfma_f32_16x16x32_bf16 v[84:87], v[238:241], v[214:217], v[84:87]
	v_mfma_f32_16x16x32_bf16 v[80:83], v[246:249], v[214:217], v[80:83]
	v_mfma_f32_16x16x32_bf16 v[76:79], v[238:241], v[222:225], v[76:79]
	v_mfma_f32_16x16x32_bf16 v[72:75], v[246:249], v[222:225], v[72:75]
	v_mfma_f32_16x16x32_bf16 v[68:71], v[238:241], v[230:233], v[68:71]
	v_mfma_f32_16x16x32_bf16 v[64:67], v[246:249], v[230:233], v[64:67]
	v_mfma_f32_16x16x32_bf16 v[92:95], v[242:245], v[210:213], v[92:95]
	v_mfma_f32_16x16x32_bf16 v[88:91], v[160:163], v[210:213], v[88:91]
	v_mfma_f32_16x16x32_bf16 v[84:87], v[242:245], v[218:221], v[84:87]
	v_mfma_f32_16x16x32_bf16 v[80:83], v[160:163], v[218:221], v[80:83]
	v_mfma_f32_16x16x32_bf16 v[76:79], v[242:245], v[226:229], v[76:79]
	v_mfma_f32_16x16x32_bf16 v[72:75], v[160:163], v[226:229], v[72:75]
	v_mfma_f32_16x16x32_bf16 v[68:71], v[242:245], v[234:237], v[68:71]
	v_mfma_f32_16x16x32_bf16 v[64:67], v[160:163], v[234:237], v[64:67]
	s_add_u32 s66, s24, s78
	s_addc_u32 s67, s25, s79
	s_add_u32 s30, s66, 0x100
	s_addc_u32 s31, s67, 0
	v_readfirstlane_b32 s70, v139
	v_lshl_add_u64 v[168:169], s[30:31], 0, v[128:129]
	s_mov_b32 m0, s70
	s_barrier
	ds_read_b128 v[206:209], v252 offset:16384
	ds_read_b128 v[210:213], v252 offset:17408
	ds_read_b128 v[214:217], v184 offset:16384
	ds_read_b128 v[218:221], v184 offset:17408
	ds_read_b128 v[222:225], v185 offset:16384
	ds_read_b128 v[226:229], v185 offset:17408
	ds_read_b128 v[230:233], v186 offset:16384
	ds_read_b128 v[234:237], v186 offset:17408
	global_load_lds_dwordx4 v[168:169], off
	v_lshl_add_u64 v[168:169], s[30:31], 0, v[130:131]
	v_readfirstlane_b32 s30, v155
	s_mov_b32 m0, s30
	s_nop 0
	global_load_lds_dwordx4 v[168:169], off
	s_barrier
	s_waitcnt lgkmcnt(0)
	v_mfma_f32_16x16x32_bf16 v[60:63], v[190:193], v[206:209], v[60:63]
	v_mfma_f32_16x16x32_bf16 v[56:59], v[198:201], v[206:209], v[56:59]
	v_mfma_f32_16x16x32_bf16 v[52:55], v[190:193], v[214:217], v[52:55]
	v_mfma_f32_16x16x32_bf16 v[48:51], v[198:201], v[214:217], v[48:51]
	v_mfma_f32_16x16x32_bf16 v[44:47], v[190:193], v[222:225], v[44:47]
	v_mfma_f32_16x16x32_bf16 v[40:43], v[198:201], v[222:225], v[40:43]
	v_mfma_f32_16x16x32_bf16 v[36:39], v[190:193], v[230:233], v[36:39]
	v_mfma_f32_16x16x32_bf16 v[32:35], v[198:201], v[230:233], v[32:35]
	v_mfma_f32_16x16x32_bf16 v[60:63], v[194:197], v[210:213], v[60:63]
	v_mfma_f32_16x16x32_bf16 v[56:59], v[202:205], v[210:213], v[56:59]
	v_mfma_f32_16x16x32_bf16 v[52:55], v[194:197], v[218:221], v[52:55]
	v_mfma_f32_16x16x32_bf16 v[48:51], v[202:205], v[218:221], v[48:51]
	v_mfma_f32_16x16x32_bf16 v[44:47], v[194:197], v[226:229], v[44:47]
	v_mfma_f32_16x16x32_bf16 v[40:43], v[202:205], v[226:229], v[40:43]
	v_mfma_f32_16x16x32_bf16 v[36:39], v[194:197], v[234:237], v[36:39]
	v_mfma_f32_16x16x32_bf16 v[32:35], v[202:205], v[234:237], v[32:35]
	s_barrier
; #define LDA(dst, b, h) _Pragma("unroll") for (int m = 0; m < 4; ++m) _Pragma("unroll") for (int k = 0; k < 2; ++k) \
;     dst[m][k] = *reinterpret_cast<const bf16x8*>((char*)SA(b, h) + lds_byte(wr * 64 + m * 16 + fr, k * 32 + fq * 8))
; #define LDB(dst, b, h) _Pragma("unroll") for (int n = 0; n < 2; ++n) _Pragma("unroll") for (int k = 0; k < 2; ++k) \
;     dst[n][k] = *reinterpret_cast<const bf16x8*>((char*)SB(b, h) + lds_byte(wc * 32 + n * 16 + fr, k * 32 + fq * 8))
; #define MMA(ai, bj, At_, Bt_) do { __builtin_amdgcn_s_setprio(1); \
;     _Pragma("unroll") for (int m = 0; m < 4; ++m) _Pragma("unroll") for (int n = 0; n < 2; ++n) _Pragma("unroll") for (int k = 0; k < 2; ++k) \
;       acc[ai][bj][m][n] = __builtin_amdgcn_mfma_f32_16x16x32_bf16(Bt_[n][k], At_[m][k], acc[ai][bj][m][n], 0, 0, 0); \
;     __builtin_amdgcn_s_setprio(0); } while (0)
; #define WAIT_V(n) asm volatile("s_waitcnt vmcnt(" #n ")" ::: "memory")
; #define WAIT_L(n) asm volatile("s_waitcnt lgkmcnt(" #n ")" ::: "memory")
; #define BAR __builtin_amdgcn_s_barrier()
; #define SCHED __builtin_amdgcn_sched_barrier(0)
; __device__ __forceinline__ void gemm_tile(const TileDesc& td, unsigned char* lds) {
;     ...
;         STAGE(SB(0, 1), Bt, ldb, bcol + HALF, t + 2);
;         WAIT_V(6); BAR; MMA(1, 1, At, B1); BAR;
;         LDB(B0, 1, 0); SCHED; LDA(At, 1, 0); STAGE(SA(0, 1), A, lda, brow + HALF, t + 2);
;         WAIT_L(8); BAR; WAIT_L(0); MMA(0, 0, At, B0); BAR; SCHED;
;         LDB(B1, 1, 1); STAGE(SB(1, 0), Bt, ldb, bcol, t + 3);
;         BAR; WAIT_L(0); MMA(0, 1, At, B1); BAR;
;         LDA(At, 1, 1); STAGE(SA(1, 0), A, lda, brow, t + 3);
	s_add_u32 s70, s80, s78
	s_addc_u32 s88, s81, s79
	s_add_u32 s30, s70, 0x100
	s_addc_u32 s31, s88, 0
	v_readfirstlane_b32 s89, v156
	v_lshl_add_u64 v[168:169], s[30:31], 0, v[132:133]
	s_mov_b32 m0, s89
	s_nop 0
	global_load_lds_dwordx4 v[168:169], off
	v_lshl_add_u64 v[168:169], s[30:31], 0, v[136:137]
	v_readfirstlane_b32 s30, v157
	s_mov_b32 m0, s30
	s_nop 0
	global_load_lds_dwordx4 v[168:169], off
	s_waitcnt vmcnt(6)
	s_barrier
	v_mfma_f32_16x16x32_bf16 v[28:31], v[238:241], v[206:209], v[28:31]
	v_mfma_f32_16x16x32_bf16 v[24:27], v[246:249], v[206:209], v[24:27]
	v_mfma_f32_16x16x32_bf16 v[20:23], v[238:241], v[214:217], v[20:23]
	v_mfma_f32_16x16x32_bf16 v[16:19], v[246:249], v[214:217], v[16:19]
	v_mfma_f32_16x16x32_bf16 v[12:15], v[238:241], v[222:225], v[12:15]
	v_mfma_f32_16x16x32_bf16 v[8:11], v[246:249], v[222:225], v[8:11]
	v_mfma_f32_16x16x32_bf16 v[4:7], v[238:241], v[230:233], v[4:7]
	v_mfma_f32_16x16x32_bf16 v[0:3], v[246:249], v[230:233], v[0:3]
	v_mfma_f32_16x16x32_bf16 v[28:31], v[242:245], v[210:213], v[28:31]
	v_mfma_f32_16x16x32_bf16 v[24:27], v[160:163], v[210:213], v[24:27]
	v_mfma_f32_16x16x32_bf16 v[20:23], v[242:245], v[218:221], v[20:23]
	v_mfma_f32_16x16x32_bf16 v[16:19], v[160:163], v[218:221], v[16:19]
	v_mfma_f32_16x16x32_bf16 v[12:15], v[242:245], v[226:229], v[12:15]
	v_mfma_f32_16x16x32_bf16 v[8:11], v[160:163], v[226:229], v[8:11]
	v_mfma_f32_16x16x32_bf16 v[4:7], v[242:245], v[234:237], v[4:7]
	v_mfma_f32_16x16x32_bf16 v[0:3], v[160:163], v[234:237], v[0:3]
	s_barrier
	ds_read_b128 v[160:163], v188
	ds_read_b128 v[190:193], v188 offset:1024
	ds_read_b128 v[194:197], v188 offset:2048
	ds_read_b128 v[198:201], v188 offset:3072
	s_add_u32 s30, s7, 0x100
	s_addc_u32 s31, s62, 0
	v_readfirstlane_b32 s7, v174
	v_lshl_add_u64 v[168:169], s[30:31], 0, v[128:129]
	s_mov_b32 m0, s7
	v_readfirstlane_b32 s7, v175
	ds_read_b128 v[202:205], v252 offset:32768
	ds_read_b128 v[206:209], v252 offset:33792
	ds_read_b128 v[210:213], v184 offset:32768
	ds_read_b128 v[214:217], v184 offset:33792
	ds_read_b128 v[218:221], v185 offset:32768
	ds_read_b128 v[222:225], v185 offset:33792
	ds_read_b128 v[226:229], v186 offset:32768
	ds_read_b128 v[230:233], v186 offset:33792
	global_load_lds_dwordx4 v[168:169], off
	v_lshl_add_u64 v[168:169], s[30:31], 0, v[130:131]
	s_mov_b32 m0, s7
	s_nop 0
	global_load_lds_dwordx4 v[168:169], off
	s_waitcnt lgkmcnt(8)
	s_barrier
	s_waitcnt lgkmcnt(0)
	v_mfma_f32_16x16x32_bf16 v[100:103], v[160:163], v[202:205], v[100:103]
	v_mfma_f32_16x16x32_bf16 v[124:127], v[194:197], v[202:205], v[124:127]
	v_mfma_f32_16x16x32_bf16 v[120:123], v[160:163], v[210:213], v[120:123]
	v_mfma_f32_16x16x32_bf16 v[116:119], v[194:197], v[210:213], v[116:119]
	v_mfma_f32_16x16x32_bf16 v[112:115], v[160:163], v[218:221], v[112:115]
	v_mfma_f32_16x16x32_bf16 v[108:111], v[194:197], v[218:221], v[108:111]
	v_mfma_f32_16x16x32_bf16 v[104:107], v[160:163], v[226:229], v[104:107]
	v_mfma_f32_16x16x32_bf16 v[96:99], v[194:197], v[226:229], v[96:99]
	v_mfma_f32_16x16x32_bf16 v[100:103], v[190:193], v[206:209], v[100:103]
	v_mfma_f32_16x16x32_bf16 v[124:127], v[198:201], v[206:209], v[124:127]
	v_mfma_f32_16x16x32_bf16 v[120:123], v[190:193], v[214:217], v[120:123]
	v_mfma_f32_16x16x32_bf16 v[116:119], v[198:201], v[214:217], v[116:119]
	v_mfma_f32_16x16x32_bf16 v[112:115], v[190:193], v[222:225], v[112:115]
	v_mfma_f32_16x16x32_bf16 v[108:111], v[198:201], v[222:225], v[108:111]
	v_mfma_f32_16x16x32_bf16 v[104:107], v[190:193], v[230:233], v[104:107]
	v_mfma_f32_16x16x32_bf16 v[96:99], v[198:201], v[230:233], v[96:99]
	s_barrier
	s_add_u32 s30, s63, 0x180
	s_addc_u32 s31, s65, 0
	v_readfirstlane_b32 s7, v176
	v_lshl_add_u64 v[168:169], s[30:31], 0, v[132:133]
	s_mov_b32 m0, s7
	v_readfirstlane_b32 s7, v177
	ds_read_b128 v[234:237], v189
	ds_read_b128 v[238:241], v189 offset:1024
	ds_read_b128 v[242:245], v189 offset:2048
	ds_read_b128 v[246:249], v189 offset:3072
	global_load_lds_dwordx4 v[168:169], off
	v_lshl_add_u64 v[168:169], s[30:31], 0, v[136:137]
	s_mov_b32 m0, s7
	s_nop 0
	global_load_lds_dwordx4 v[168:169], off
	s_barrier
; #define LDA(dst, b, h) _Pragma("unroll") for (int m = 0; m < 4; ++m) _Pragma("unroll") for (int k = 0; k < 2; ++k) \
;     dst[m][k] = *reinterpret_cast<const bf16x8*>((char*)SA(b, h) + lds_byte(wr * 64 + m * 16 + fr, k * 32 + fq * 8))
; #define MMA(ai, bj, At_, Bt_) do { __builtin_amdgcn_s_setprio(1); \
;     _Pragma("unroll") for (int m = 0; m < 4; ++m) _Pragma("unroll") for (int n = 0; n < 2; ++n) _Pragma("unroll") for (int k = 0; k < 2; ++k) \
;       acc[ai][bj][m][n] = __builtin_amdgcn_mfma_f32_16x16x32_bf16(Bt_[n][k], At_[m][k], acc[ai][bj][m][n], 0, 0, 0); \
;     __builtin_amdgcn_s_setprio(0); } while (0)
; #define WAIT_V(n) asm volatile("s_waitcnt vmcnt(" #n ")" ::: "memory")
; #define WAIT_L(n) asm volatile("s_waitcnt lgkmcnt(" #n ")" ::: "memory")
; #define BAR __builtin_amdgcn_s_barrier()
; #define SCHED __builtin_amdgcn_sched_barrier(0)
; __device__ __forceinline__ void gemm_tile(const TileDesc& td, unsigned char* lds) {
;     ...
;         LDA(At, 1, 1); STAGE(SA(1, 0), A, lda, brow, t + 3);
;         BAR; WAIT_L(0); MMA(1, 0, At, B0); BAR; SCHED;
;         STAGE(SB(1, 1), Bt, ldb, bcol + HALF, t + 3);
;         WAIT_V(6); BAR; MMA(1, 1, At, B1); BAR;
;     }
	s_waitcnt lgkmcnt(0)
	v_mfma_f32_16x16x32_bf16 v[92:95], v[234:237], v[202:205], v[92:95]
	v_mfma_f32_16x16x32_bf16 v[88:91], v[242:245], v[202:205], v[88:91]
	v_mfma_f32_16x16x32_bf16 v[84:87], v[234:237], v[210:213], v[84:87]
	v_mfma_f32_16x16x32_bf16 v[80:83], v[242:245], v[210:213], v[80:83]
	v_mfma_f32_16x16x32_bf16 v[76:79], v[234:237], v[218:221], v[76:79]
	v_mfma_f32_16x16x32_bf16 v[72:75], v[242:245], v[218:221], v[72:75]
	v_mfma_f32_16x16x32_bf16 v[68:71], v[234:237], v[226:229], v[68:71]
	v_mfma_f32_16x16x32_bf16 v[64:67], v[242:245], v[226:229], v[64:67]
	v_mfma_f32_16x16x32_bf16 v[92:95], v[238:241], v[206:209], v[92:95]
	v_mfma_f32_16x16x32_bf16 v[88:91], v[246:249], v[206:209], v[88:91]
	v_mfma_f32_16x16x32_bf16 v[84:87], v[238:241], v[214:217], v[84:87]
	v_mfma_f32_16x16x32_bf16 v[80:83], v[246:249], v[214:217], v[80:83]
	v_mfma_f32_16x16x32_bf16 v[76:79], v[238:241], v[222:225], v[76:79]
	v_mfma_f32_16x16x32_bf16 v[72:75], v[246:249], v[222:225], v[72:75]
	v_mfma_f32_16x16x32_bf16 v[68:71], v[238:241], v[230:233], v[68:71]
	v_mfma_f32_16x16x32_bf16 v[64:67], v[246:249], v[230:233], v[64:67]
	s_add_u32 s30, s66, 0x180
	s_addc_u32 s31, s67, 0
	v_readfirstlane_b32 s7, v178
	v_lshl_add_u64 v[168:169], s[30:31], 0, v[128:129]
	s_mov_b32 m0, s7
	v_readfirstlane_b32 s7, v179
	s_barrier
	ds_read_b128 v[202:205], v252 offset:49152
	ds_read_b128 v[206:209], v252 offset:50176
	ds_read_b128 v[210:213], v184 offset:49152
	ds_read_b128 v[214:217], v184 offset:50176
	ds_read_b128 v[218:221], v185 offset:49152
	ds_read_b128 v[222:225], v185 offset:50176
	ds_read_b128 v[226:229], v186 offset:49152
	ds_read_b128 v[230:233], v186 offset:50176
	global_load_lds_dwordx4 v[168:169], off
	v_lshl_add_u64 v[168:169], s[30:31], 0, v[130:131]
	s_mov_b32 m0, s7
	s_nop 0
	global_load_lds_dwordx4 v[168:169], off
	s_barrier
	s_waitcnt lgkmcnt(0)
	v_mfma_f32_16x16x32_bf16 v[60:63], v[160:163], v[202:205], v[60:63]
	v_mfma_f32_16x16x32_bf16 v[56:59], v[194:197], v[202:205], v[56:59]
	v_mfma_f32_16x16x32_bf16 v[52:55], v[160:163], v[210:213], v[52:55]
	v_mfma_f32_16x16x32_bf16 v[48:51], v[194:197], v[210:213], v[48:51]
	v_mfma_f32_16x16x32_bf16 v[44:47], v[160:163], v[218:221], v[44:47]
	v_mfma_f32_16x16x32_bf16 v[40:43], v[194:197], v[218:221], v[40:43]
	v_mfma_f32_16x16x32_bf16 v[36:39], v[160:163], v[226:229], v[36:39]
	v_mfma_f32_16x16x32_bf16 v[32:35], v[194:197], v[226:229], v[32:35]
	v_mfma_f32_16x16x32_bf16 v[60:63], v[190:193], v[206:209], v[60:63]
	v_mfma_f32_16x16x32_bf16 v[56:59], v[198:201], v[206:209], v[56:59]
	v_mfma_f32_16x16x32_bf16 v[52:55], v[190:193], v[214:217], v[52:55]
	v_mfma_f32_16x16x32_bf16 v[48:51], v[198:201], v[214:217], v[48:51]
	v_mfma_f32_16x16x32_bf16 v[44:47], v[190:193], v[222:225], v[44:47]
	v_mfma_f32_16x16x32_bf16 v[40:43], v[198:201], v[222:225], v[40:43]
	v_mfma_f32_16x16x32_bf16 v[36:39], v[190:193], v[230:233], v[36:39]
	v_mfma_f32_16x16x32_bf16 v[32:35], v[198:201], v[230:233], v[32:35]
	s_barrier
	s_add_u32 s30, s70, 0x180
	s_addc_u32 s31, s88, 0
	v_readfirstlane_b32 s7, v180
	v_lshl_add_u64 v[160:161], s[30:31], 0, v[132:133]
	s_mov_b32 m0, s7
	v_readfirstlane_b32 s7, v181
	global_load_lds_dwordx4 v[160:161], off
	v_lshl_add_u64 v[160:161], s[30:31], 0, v[136:137]
	s_mov_b32 m0, s7
	s_nop 0
	global_load_lds_dwordx4 v[160:161], off
	s_add_u32 s78, s78, 0x100
	s_addc_u32 s79, s79, 0
	s_cmp_lt_i32 s3, s2
	s_waitcnt vmcnt(6)
	s_barrier
	v_mfma_f32_16x16x32_bf16 v[28:31], v[234:237], v[202:205], v[28:31]
	v_mfma_f32_16x16x32_bf16 v[24:27], v[242:245], v[202:205], v[24:27]
	v_mfma_f32_16x16x32_bf16 v[20:23], v[234:237], v[210:213], v[20:23]
	v_mfma_f32_16x16x32_bf16 v[16:19], v[242:245], v[210:213], v[16:19]
	v_mfma_f32_16x16x32_bf16 v[12:15], v[234:237], v[218:221], v[12:15]
	v_mfma_f32_16x16x32_bf16 v[8:11], v[242:245], v[218:221], v[8:11]
	v_mfma_f32_16x16x32_bf16 v[4:7], v[234:237], v[226:229], v[4:7]
	v_mfma_f32_16x16x32_bf16 v[0:3], v[242:245], v[226:229], v[0:3]
	v_mfma_f32_16x16x32_bf16 v[28:31], v[238:241], v[206:209], v[28:31]
	v_mfma_f32_16x16x32_bf16 v[24:27], v[246:249], v[206:209], v[24:27]
	v_mfma_f32_16x16x32_bf16 v[20:23], v[238:241], v[214:217], v[20:23]
	v_mfma_f32_16x16x32_bf16 v[16:19], v[246:249], v[214:217], v[16:19]
	v_mfma_f32_16x16x32_bf16 v[12:15], v[238:241], v[222:225], v[12:15]
	v_mfma_f32_16x16x32_bf16 v[8:11], v[246:249], v[222:225], v[8:11]
	v_mfma_f32_16x16x32_bf16 v[4:7], v[238:241], v[230:233], v[4:7]
	v_mfma_f32_16x16x32_bf16 v[0:3], v[246:249], v[230:233], v[0:3]
	s_barrier
	s_cbranch_scc1 .LBB0_247
	v_or_b32_e32 v182, 0x400, v138
	v_or_b32_e32 v183, 0x800, v138
	v_or_b32_e32 v184, 0xc00, v138
	v_mov_b32_e32 v185, v154
	v_mov_b32_e32 v235, v159
	v_mov_b32_e32 v236, v172
	v_mov_b32_e32 v172, v170
	v_mov_b32_e32 v170, v173
	v_mov_b32_e32 v237, v165
	v_mov_b32_e32 v165, v167
	v_mov_b32_e32 v238, v135
	v_mov_b32_e32 v135, v171
	v_mov_b32_e32 v167, 0x42000000
